# code placement: PEER phase code shifted by 4 bytes (gather and selection loops at the other 8-byte phase)
# baseline (speedup 1.0000x reference)
.LBB0_690:
	s_andn2_saveexec_b64 s[6:7], s[6:7]
	s_cbranch_execz .LBB0_706
	v_mov_b32_e32 v1, s48
	v_add_co_u32_e32 v2, vcc, 0x3000, v1
	v_mov_b32_e32 v1, s49
	buffer_wbl2 sc1
	s_waitcnt vmcnt(0)
	v_addc_co_u32_e32 v3, vcc, 0, v1, vcc
	v_mov_b32_e32 v1, 1
	flat_atomic_add v1, v[2:3], v1 offset:1024 sc0
	v_cvt_f32_u32_e32 v2, v0
	v_sub_u32_e32 v3, 0, v0
	s_mov_b64 s[10:11], -1
	v_rcp_iflag_f32_e32 v2, v2
	s_nop 0
	v_mul_f32_e32 v2, 0x4f7ffffe, v2
	v_cvt_u32_f32_e32 v2, v2
	v_mul_lo_u32 v3, v3, v2
	v_mul_hi_u32 v3, v2, v3
	v_add_u32_e32 v2, v2, v3
	s_waitcnt vmcnt(0) lgkmcnt(0)
	v_mul_hi_u32 v2, v1, v2
	v_mul_lo_u32 v3, v2, v0
	v_sub_u32_e32 v3, v1, v3
	v_cmp_ge_u32_e32 vcc, v3, v0
	v_add_u32_e32 v4, 1, v2
	s_nop 0
	v_cndmask_b32_e32 v2, v2, v4, vcc
	v_sub_u32_e32 v4, v3, v0
	v_cndmask_b32_e32 v3, v3, v4, vcc
	v_cmp_ge_u32_e32 vcc, v3, v0
	v_add_u32_e32 v3, 1, v2
	s_nop 0
	v_cndmask_b32_e32 v2, v2, v3, vcc
	v_add_u32_e32 v3, 1, v1
	v_mad_u64_u32 v[0:1], s[6:7], v0, v2, v[0:1]
	s_add_u32 s6, s48, 0x3500
	s_addc_u32 s7, s49, 0
	v_cmp_ne_u32_e32 vcc, v3, v0
	s_nop 0
	v_mov_b64_e32 v[0:1], s[6:7]
	s_and_saveexec_b64 s[8:9], vcc
	s_cbranch_execz .LBB0_703
	v_mov_b64_e32 v[0:1], s[6:7]
	flat_load_dword v0, v[0:1] sc1
	s_mov_b64 s[14:15], 0
	s_waitcnt vmcnt(0) lgkmcnt(0)
	v_cmp_eq_u32_e32 vcc, v0, v2
	s_and_saveexec_b64 s[12:13], vcc
	s_cbranch_execz .LBB0_702
	s_add_u32 s10, s48, 0x200
	s_addc_u32 s11, s49, 0
	s_mov_b32 s27, 1
	s_branch .LBB0_695
